# swa attention: band masking skipped (wave-uniform test) for key tiles that lie fully inside the window of the wave's 32 query rows
# speedup vs baseline: 1.0038x; 1.0010x over previous
.LBB0_430:
	s_add_i32 s2, s47, -3
	s_cmp_lt_i32 s2, s44
	s_cselect_b64 s[14:15], -1, 0
	s_cmp_ge_i32 s2, s44
	s_cselect_b64 s[16:17], -1, 0
	s_and_b64 vcc, exec, s[16:17]
	s_cbranch_vccnz .LBB0_432
	s_add_i32 s2, s12, s46
	s_add_i32 s3, s2, 0xffffff40
	s_addk_i32 s2, 0xff7f
	s_add_i32 s98, s3, 0xffffffe1
	s_add_i32 s99, s3, 0x5e
	v_cmp_ge_i32_e32 vcc, s2, v116
	v_cmp_le_i32_e64 s[2:3], s3, v117
	s_and_b64 s[2:3], vcc, s[2:3]
	s_andn2_b64 s[16:17], s[16:17], exec
	s_and_b64 s[2:3], s[2:3], exec
	s_or_b64 s[16:17], s[16:17], s[2:3]
	v_cmp_ge_i32_e32 vcc, s98, v116
	v_cmp_le_i32_e64 s[98:99], s99, v117
	s_and_b64 s[98:99], vcc, s[98:99]
	s_andn2_b64 s[14:15], s[14:15], s[98:99]

.LBB0_440:
	s_add_i32 s2, s47, -2
	s_cmp_lt_i32 s2, s44
	s_cselect_b64 s[14:15], -1, 0
	s_cmp_ge_i32 s2, s44
	s_cselect_b64 s[16:17], -1, 0
	s_and_b64 vcc, exec, s[16:17]
	s_cbranch_vccnz .LBB0_442
	s_add_i32 s2, s12, s46
	s_add_i32 s3, s2, 0xffffff80
	s_addk_i32 s2, 0xffbf
	s_add_i32 s98, s3, 0xffffffe1
	s_add_i32 s99, s3, 0x5e
	v_cmp_ge_i32_e32 vcc, s2, v116
	v_cmp_le_i32_e64 s[2:3], s3, v117
	s_and_b64 s[2:3], vcc, s[2:3]
	s_andn2_b64 s[16:17], s[16:17], exec
	s_and_b64 s[2:3], s[2:3], exec
	s_or_b64 s[16:17], s[16:17], s[2:3]
	v_cmp_ge_i32_e32 vcc, s98, v116
	v_cmp_le_i32_e64 s[98:99], s99, v117
	s_and_b64 s[98:99], vcc, s[98:99]
	s_andn2_b64 s[14:15], s[14:15], s[98:99]
